# GEMM K-loop: scalar address arithmetic of the loop top rotated into the MFMA stream of the previous iteration's last compute segment
# baseline (speedup 1.0000x reference)
; #define PG8_STAGE(bufoff, gbase, voff) do { _Pragma("unroll") for (int _i = 0; _i < 2; ++_i) \
;         __builtin_amdgcn_global_load_lds((const unsigned*)((const char*)(gbase) + (voff)[_i]), (PG8_LAS unsigned*)(lds + (bufoff) + ldsw + _i * 8192), 16, 0, 0); } while (0)
; #define PG8_LDA(dst, b, h) do { _Pragma("unroll") for (int m = 0; m < 4; ++m) _Pragma("unroll") for (int k = 0; k < 2; ++k) dst[m][k] = *(const PG8_LAS bf16x8*)(lds + PG8_SA(b, h) + aoff + m * 2048 + k * 1024); } while (0)
; #define PG8_LDB(dst, b, h) do { _Pragma("unroll") for (int n = 0; n < 2; ++n) _Pragma("unroll") for (int k = 0; k < 2; ++k) dst[n][k] = *(const PG8_LAS bf16x8*)(lds + PG8_SB(b, h) + boff + n * 2048 + k * 1024); } while (0)
; #define PG8_WAIT_V(n) asm volatile("s_waitcnt vmcnt(" #n ")" ::: "memory")
; #define PG8_WAIT_L(n) asm volatile("s_waitcnt lgkmcnt(" #n ")" ::: "memory")
; #define PG8_BAR __builtin_amdgcn_s_barrier()
; template <class Epi, class Sched, bool ALIGN_EPI = false, bool SP2 = false>
; __device__ __forceinline__ void gemm_phase(PG8_LAS unsigned char* lds, const Gemm g, const Sched& S, const Epi& E) {
;     ...
;         const bool has_next = S.next(ui + 1, nxt);
;         const char* nA = has_next ? (const char*)g.A + (size_t)nxt.pm * tstep + (size_t)(nxt.ko / BK) * kstep : cA; const char* nB = has_next ? (const char*)g.Bt + (size_t)nxt.pn * tstep + (size_t)(nxt.ko / BK) * kstep : cB;
;         for (int t = 0; t < nt; t += 2) {
;             const bool last = (t == nt - 2);
;             const char* a1 = cA + (size_t)(t + 1) * kstep;
;             const char* a2 = last ? nA : cA + (size_t)(t + 2) * kstep; const char* b2 = last ? nB : cB + (size_t)(t + 2) * kstep;
;             const char* a3 = a2 + kstep; const char* b3 = b2 + kstep;
;             if (last && has_next) S.a_ready(nxt);
;             if constexpr (SP2) {
;             PG8_LDB(B0, 0, 0); PG8_LDB(B1, 0, 1); PG8_SCHED; PG8_LDA(At, 0, 0); PG8_STAGE(PG8_SA(1, 1), a1 + hstep, voffA);
;             PG8_WAIT_V(8); PG8_WAIT_L(0); PG8_BAR; PG8_MMA(0, 0, At, B0); PG8_MMA(0, 1, At, B1); PG8_BAR; PG8_SCHED;
;     ...
; #pragma unroll
;         for (int a = 0; a < 2; ++a)
; #pragma unroll
;             for (int b = 0; b < 2; ++b)
; #pragma unroll
;                 for (int m = 0; m < 4; ++m)
; #pragma unroll
;                     for (int n = 0; n < 2; ++n) acc[a][b][m][n] = (f32x4){0.f, 0.f, 0.f, 0.f};
.LBB0_161:
	s_add_u32 s25, s10, s21
	v_mov_b32_e32 v0, 0
	s_addc_u32 s26, s11, 0
	s_mov_b64 s[12:13], 0
	v_mov_b32_e32 v1, v0
	v_mov_b32_e32 v2, v0
	v_mov_b32_e32 v3, v0
	v_mov_b32_e32 v8, v0
	v_mov_b32_e32 v9, v0
	v_mov_b32_e32 v10, v0
	v_mov_b32_e32 v11, v0
	v_mov_b32_e32 v16, v0
	v_mov_b32_e32 v17, v0
	v_mov_b32_e32 v18, v0
	v_mov_b32_e32 v19, v0
	v_mov_b32_e32 v24, v0
	v_mov_b32_e32 v25, v0
	v_mov_b32_e32 v26, v0
	v_mov_b32_e32 v27, v0
	v_mov_b32_e32 v32, v0
	v_mov_b32_e32 v33, v0
	v_mov_b32_e32 v34, v0
	v_mov_b32_e32 v35, v0
	v_mov_b32_e32 v40, v0
	v_mov_b32_e32 v41, v0
	v_mov_b32_e32 v42, v0
	v_mov_b32_e32 v43, v0
	v_mov_b32_e32 v48, v0
	v_mov_b32_e32 v49, v0
	v_mov_b32_e32 v50, v0
	v_mov_b32_e32 v51, v0
	v_mov_b32_e32 v56, v0
	v_mov_b32_e32 v57, v0
	v_mov_b32_e32 v58, v0
	v_mov_b32_e32 v59, v0
	v_mov_b32_e32 v4, v0
	v_mov_b32_e32 v5, v0
	v_mov_b32_e32 v6, v0
	v_mov_b32_e32 v7, v0
	v_mov_b32_e32 v12, v0
	v_mov_b32_e32 v13, v0
	v_mov_b32_e32 v14, v0
	v_mov_b32_e32 v15, v0
	v_mov_b32_e32 v20, v0
	v_mov_b32_e32 v21, v0
	v_mov_b32_e32 v22, v0
	v_mov_b32_e32 v23, v0
	v_mov_b32_e32 v28, v0
	v_mov_b32_e32 v29, v0
	v_mov_b32_e32 v30, v0
	v_mov_b32_e32 v31, v0
	v_mov_b32_e32 v36, v0
	v_mov_b32_e32 v37, v0
	v_mov_b32_e32 v38, v0
	v_mov_b32_e32 v39, v0
	v_mov_b32_e32 v44, v0
	v_mov_b32_e32 v45, v0
	v_mov_b32_e32 v46, v0
	v_mov_b32_e32 v47, v0
	v_mov_b32_e32 v52, v0
	v_mov_b32_e32 v53, v0
	v_mov_b32_e32 v54, v0
	v_mov_b32_e32 v55, v0
	v_mov_b32_e32 v60, v0
	v_mov_b32_e32 v61, v0
	v_mov_b32_e32 v62, v0
	v_mov_b32_e32 v63, v0
	v_mov_b32_e32 v64, v0
	v_mov_b32_e32 v65, v0
	v_mov_b32_e32 v66, v0
	v_mov_b32_e32 v67, v0
	v_mov_b32_e32 v72, v0
	v_mov_b32_e32 v73, v0
	v_mov_b32_e32 v74, v0
	v_mov_b32_e32 v75, v0
	v_mov_b32_e32 v80, v0
	v_mov_b32_e32 v81, v0
	v_mov_b32_e32 v82, v0
	v_mov_b32_e32 v83, v0
	v_mov_b32_e32 v88, v0
	v_mov_b32_e32 v89, v0
	v_mov_b32_e32 v90, v0
	v_mov_b32_e32 v91, v0
	v_mov_b32_e32 v96, v0
	v_mov_b32_e32 v97, v0
	v_mov_b32_e32 v98, v0
	v_mov_b32_e32 v99, v0
	v_mov_b32_e32 v104, v0
	v_mov_b32_e32 v105, v0
	v_mov_b32_e32 v106, v0
	v_mov_b32_e32 v107, v0
	s_waitcnt vmcnt(0)
	v_mov_b32_e32 v112, v0
	v_mov_b32_e32 v113, v0
	v_mov_b32_e32 v114, v0
	v_mov_b32_e32 v115, v0
	v_mov_b32_e32 v120, v0
	v_mov_b32_e32 v121, v0
	v_mov_b32_e32 v122, v0
	v_mov_b32_e32 v123, v0
	v_mov_b32_e32 v68, v0
	v_mov_b32_e32 v69, v0
	v_mov_b32_e32 v70, v0
	v_mov_b32_e32 v71, v0
	v_mov_b32_e32 v76, v0
	v_mov_b32_e32 v77, v0
	v_mov_b32_e32 v78, v0
	v_mov_b32_e32 v79, v0
	v_mov_b32_e32 v84, v0
	v_mov_b32_e32 v85, v0
	v_mov_b32_e32 v86, v0
	v_mov_b32_e32 v87, v0
	v_mov_b32_e32 v92, v0
	v_mov_b32_e32 v93, v0
	v_mov_b32_e32 v94, v0
	v_mov_b32_e32 v95, v0
	v_mov_b32_e32 v100, v0
	v_mov_b32_e32 v101, v0
	v_mov_b32_e32 v102, v0
	v_mov_b32_e32 v103, v0
	v_mov_b32_e32 v108, v0
	v_mov_b32_e32 v109, v0
	v_mov_b32_e32 v110, v0
	v_mov_b32_e32 v111, v0
	v_mov_b32_e32 v116, v0
	v_mov_b32_e32 v117, v0
	v_mov_b32_e32 v118, v0
	v_mov_b32_e32 v119, v0
	v_mov_b32_e32 v124, v0
	v_mov_b32_e32 v125, v0
	v_mov_b32_e32 v126, v0
	v_mov_b32_e32 v127, v0
	s_add_u32 s94, s12, 1
	s_addc_u32 s95, s13, 0
	s_add_u32 s14, s12, 2
	s_addc_u32 s15, s13, 0
	s_lshl_b64 s[30:31], s[14:15], s60
	s_add_u32 s13, s10, s30
	s_addc_u32 s29, s11, s31
	s_add_u32 s30, s8, s30
	s_addc_u32 s31, s9, s31
	s_cmp_eq_u32 s2, s12
	s_cselect_b32 s92, s88, s13
	s_cselect_b32 s93, s89, s29
	s_cselect_b32 s30, s90, s30
	s_cselect_b32 s31, s91, s31
	s_add_u32 s12, s92, s20
	s_addc_u32 s13, s93, 0
	s_add_i32 s29, 0, 0x10000
	s_add_i32 s50, 0, 0x14000
	s_lshl_b64 s[94:95], s[94:95], s60
	s_add_u32 s94, s25, s94
	s_addc_u32 s95, s26, s95
.LBB0_162:
	v_add_u32_e32 v140, s29, v231
	v_add_u32_e32 v156, s50, v231
	ds_read_b128 v[128:131], v140
	ds_read_b128 v[132:135], v140 offset:1024
	ds_read_b128 v[136:139], v140 offset:2048
	ds_read_b128 v[140:143], v140 offset:3072
	ds_read_b128 v[144:147], v156
	ds_read_b128 v[148:151], v156 offset:1024
	ds_read_b128 v[152:155], v156 offset:2048
	ds_read_b128 v[156:159], v156 offset:3072
	v_lshl_add_u64 v[214:215], s[94:95], 0, v[174:175]
	s_add_i32 m0, s18, 0xc000
	ds_read_b128 v[160:163], v233
	ds_read_b128 v[210:213], v233 offset:1024
	ds_read_b128 v[234:237], v233 offset:2048
	ds_read_b128 v[238:241], v233 offset:3072
	ds_read_b128 v[242:245], v233 offset:4096
	ds_read_b128 v[246:249], v233 offset:5120
	ds_read_b128 v[250:253], v233 offset:6144
	ds_read_b128 v[218:221], v233 offset:7168
	global_load_lds_dwordx4 v[214:215], off
	v_lshl_add_u64 v[214:215], s[94:95], 0, v[176:177]
	s_add_i32 m0, s18, 0xe000
	s_nop 0
	global_load_lds_dwordx4 v[214:215], off
	s_waitcnt vmcnt(8)
	s_waitcnt lgkmcnt(0)
	s_barrier
; #define PG8_STAGE(bufoff, gbase, voff) do { _Pragma("unroll") for (int _i = 0; _i < 2; ++_i) \
;         __builtin_amdgcn_global_load_lds((const unsigned*)((const char*)(gbase) + (voff)[_i]), (PG8_LAS unsigned*)(lds + (bufoff) + ldsw + _i * 8192), 16, 0, 0); } while (0)
; #define PG8_LDA(dst, b, h) do { _Pragma("unroll") for (int m = 0; m < 4; ++m) _Pragma("unroll") for (int k = 0; k < 2; ++k) dst[m][k] = *(const PG8_LAS bf16x8*)(lds + PG8_SA(b, h) + aoff + m * 2048 + k * 1024); } while (0)
; #define PG8_LDB(dst, b, h) do { _Pragma("unroll") for (int n = 0; n < 2; ++n) _Pragma("unroll") for (int k = 0; k < 2; ++k) dst[n][k] = *(const PG8_LAS bf16x8*)(lds + PG8_SB(b, h) + boff + n * 2048 + k * 1024); } while (0)
; #define PG8_MMA(ai, bj, At, Bt) do { __builtin_amdgcn_s_setprio(1); _Pragma("unroll") for (int m = 0; m < 4; ++m) _Pragma("unroll") for (int n = 0; n < 2; ++n) _Pragma("unroll") for (int k = 0; k < 2; ++k) \
;         acc[ai][bj][m][n] = __builtin_amdgcn_mfma_f32_16x16x32_bf16(Bt[n][k], At[m][k], acc[ai][bj][m][n], 0, 0, 0); __builtin_amdgcn_s_setprio(0); } while (0)
; #define PG8_WAIT_V(n) asm volatile("s_waitcnt vmcnt(" #n ")" ::: "memory")
; #define PG8_WAIT_L(n) asm volatile("s_waitcnt lgkmcnt(" #n ")" ::: "memory")
; #define PG8_BAR __builtin_amdgcn_s_barrier()
; #define PG8_SCHED __builtin_amdgcn_sched_barrier(0)
; template <class Epi, class Sched, bool ALIGN_EPI = false, bool SP2 = false>
; __device__ __forceinline__ void gemm_phase(PG8_LAS unsigned char* lds, const Gemm g, const Sched& S, const Epi& E) {
;     ...
;             PG8_WAIT_V(8); PG8_WAIT_L(0); PG8_BAR; PG8_MMA(0, 0, At, B0); PG8_MMA(0, 1, At, B1); PG8_BAR; PG8_SCHED;
;             PG8_LDA(At, 0, 1); PG8_STAGE(PG8_SB(0, 0), b2, voffB); PG8_STAGE(PG8_SB(0, 1), b2 + hstep, voffB); PG8_STAGE(PG8_SA(0, 0), a2, voffA);
;             PG8_WAIT_V(8); PG8_WAIT_L(0); PG8_BAR; PG8_MMA(1, 0, At, B0); PG8_MMA(1, 1, At, B1); PG8_BAR; PG8_SCHED;
;             PG8_LDB(B0, 1, 0); PG8_LDB(B1, 1, 1); PG8_SCHED; PG8_LDA(At, 1, 0); PG8_STAGE(PG8_SA(0, 1), a2 + hstep, voffA);
;             PG8_WAIT_V(8); PG8_WAIT_L(0); PG8_BAR; PG8_MMA(0, 0, At, B0); PG8_MMA(0, 1, At, B1); PG8_BAR; PG8_SCHED;
	s_setprio 1
	s_waitcnt lgkmcnt(0)
	v_mfma_f32_16x16x32_bf16 v[124:127], v[128:131], v[160:163], v[124:127]
	v_mfma_f32_16x16x32_bf16 v[116:119], v[136:139], v[160:163], v[116:119]
	v_mfma_f32_16x16x32_bf16 v[108:111], v[128:131], v[234:237], v[108:111]
	v_mfma_f32_16x16x32_bf16 v[100:103], v[136:139], v[234:237], v[100:103]
	v_mfma_f32_16x16x32_bf16 v[92:95], v[128:131], v[242:245], v[92:95]
	v_mfma_f32_16x16x32_bf16 v[84:87], v[136:139], v[242:245], v[84:87]
	v_mfma_f32_16x16x32_bf16 v[76:79], v[128:131], v[250:253], v[76:79]
	v_mfma_f32_16x16x32_bf16 v[68:71], v[136:139], v[250:253], v[68:71]
	v_mfma_f32_16x16x32_bf16 v[124:127], v[132:135], v[210:213], v[124:127]
	v_mfma_f32_16x16x32_bf16 v[116:119], v[140:143], v[210:213], v[116:119]
	v_mfma_f32_16x16x32_bf16 v[108:111], v[132:135], v[238:241], v[108:111]
	v_mfma_f32_16x16x32_bf16 v[100:103], v[140:143], v[238:241], v[100:103]
	v_mfma_f32_16x16x32_bf16 v[92:95], v[132:135], v[246:249], v[92:95]
	v_mfma_f32_16x16x32_bf16 v[84:87], v[140:143], v[246:249], v[84:87]
	v_mfma_f32_16x16x32_bf16 v[76:79], v[132:135], v[218:221], v[76:79]
	v_mfma_f32_16x16x32_bf16 v[68:71], v[140:143], v[218:221], v[68:71]
	s_setprio 0
	s_setprio 1
	v_mfma_f32_16x16x32_bf16 v[120:123], v[144:147], v[160:163], v[120:123]
	v_mfma_f32_16x16x32_bf16 v[112:115], v[152:155], v[160:163], v[112:115]
	v_mfma_f32_16x16x32_bf16 v[104:107], v[144:147], v[234:237], v[104:107]
	v_mfma_f32_16x16x32_bf16 v[96:99], v[152:155], v[234:237], v[96:99]
	v_mfma_f32_16x16x32_bf16 v[88:91], v[144:147], v[242:245], v[88:91]
	v_mfma_f32_16x16x32_bf16 v[80:83], v[152:155], v[242:245], v[80:83]
	v_mfma_f32_16x16x32_bf16 v[72:75], v[144:147], v[250:253], v[72:75]
	v_mfma_f32_16x16x32_bf16 v[64:67], v[152:155], v[250:253], v[64:67]
	v_mfma_f32_16x16x32_bf16 v[120:123], v[148:151], v[210:213], v[120:123]
	v_mfma_f32_16x16x32_bf16 v[112:115], v[156:159], v[210:213], v[112:115]
	v_mfma_f32_16x16x32_bf16 v[104:107], v[148:151], v[238:241], v[104:107]
	v_mfma_f32_16x16x32_bf16 v[96:99], v[156:159], v[238:241], v[96:99]
	v_mfma_f32_16x16x32_bf16 v[88:91], v[148:151], v[246:249], v[88:91]
	v_mfma_f32_16x16x32_bf16 v[80:83], v[156:159], v[246:249], v[80:83]
	v_mfma_f32_16x16x32_bf16 v[72:75], v[148:151], v[218:221], v[72:75]
	v_mfma_f32_16x16x32_bf16 v[64:67], v[156:159], v[218:221], v[64:67]
	s_setprio 0
	s_barrier
	s_add_i32 s29, s29, s77
	v_lshl_add_u64 v[214:215], s[30:31], 0, v[174:175]
	s_mov_b32 m0, s29
	ds_read_b128 v[160:163], v233 offset:16384
	ds_read_b128 v[210:213], v233 offset:17408
	ds_read_b128 v[218:221], v233 offset:18432
	ds_read_b128 v[234:237], v233 offset:19456
	ds_read_b128 v[238:241], v233 offset:20480
	ds_read_b128 v[242:245], v233 offset:21504
	ds_read_b128 v[246:249], v233 offset:22528
	ds_read_b128 v[250:253], v233 offset:23552
	global_load_lds_dwordx4 v[214:215], off
	s_add_i32 m0, s29, 0x2000
	s_add_u32 s94, s30, s21
	v_lshl_add_u64 v[214:215], s[30:31], 0, v[176:177]
	s_addc_u32 s95, s31, 0
	s_add_i32 s29, s50, s77
	global_load_lds_dwordx4 v[214:215], off
	v_lshl_add_u64 v[214:215], s[94:95], 0, v[174:175]
	s_mov_b32 m0, s29
	s_nop 0
	global_load_lds_dwordx4 v[214:215], off
	v_lshl_add_u64 v[214:215], s[94:95], 0, v[176:177]
	s_add_i32 m0, s29, 0x2000
	s_nop 0
	global_load_lds_dwordx4 v[214:215], off
	v_lshl_add_u64 v[214:215], s[92:93], 0, v[174:175]
	s_mov_b32 m0, s18
	s_nop 0
	global_load_lds_dwordx4 v[214:215], off
	v_lshl_add_u64 v[214:215], s[92:93], 0, v[176:177]
	s_mov_b32 m0, s19
	s_nop 0
	global_load_lds_dwordx4 v[214:215], off
	s_waitcnt vmcnt(8)
	s_waitcnt lgkmcnt(0)
	s_barrier
	s_setprio 1
	s_waitcnt lgkmcnt(0)
	v_mfma_f32_16x16x32_bf16 v[60:63], v[128:131], v[160:163], v[60:63]
	v_mfma_f32_16x16x32_bf16 v[52:55], v[136:139], v[160:163], v[52:55]
	v_mfma_f32_16x16x32_bf16 v[44:47], v[128:131], v[218:221], v[44:47]
	v_mfma_f32_16x16x32_bf16 v[36:39], v[136:139], v[218:221], v[36:39]
	v_mfma_f32_16x16x32_bf16 v[28:31], v[128:131], v[238:241], v[28:31]
	v_mfma_f32_16x16x32_bf16 v[20:23], v[136:139], v[238:241], v[20:23]
	v_mfma_f32_16x16x32_bf16 v[12:15], v[128:131], v[246:249], v[12:15]
	v_mfma_f32_16x16x32_bf16 v[4:7], v[136:139], v[246:249], v[4:7]
	v_mfma_f32_16x16x32_bf16 v[60:63], v[132:135], v[210:213], v[60:63]
	v_mfma_f32_16x16x32_bf16 v[52:55], v[140:143], v[210:213], v[52:55]
	v_mfma_f32_16x16x32_bf16 v[44:47], v[132:135], v[234:237], v[44:47]
	v_mfma_f32_16x16x32_bf16 v[36:39], v[140:143], v[234:237], v[36:39]
	v_mfma_f32_16x16x32_bf16 v[28:31], v[132:135], v[242:245], v[28:31]
	v_mfma_f32_16x16x32_bf16 v[20:23], v[140:143], v[242:245], v[20:23]
	v_mfma_f32_16x16x32_bf16 v[12:15], v[132:135], v[250:253], v[12:15]
	v_mfma_f32_16x16x32_bf16 v[4:7], v[140:143], v[250:253], v[4:7]
	s_setprio 0
	s_setprio 1
	v_mfma_f32_16x16x32_bf16 v[56:59], v[144:147], v[160:163], v[56:59]
	v_mfma_f32_16x16x32_bf16 v[48:51], v[152:155], v[160:163], v[48:51]
	v_mfma_f32_16x16x32_bf16 v[40:43], v[144:147], v[218:221], v[40:43]
	v_mfma_f32_16x16x32_bf16 v[32:35], v[152:155], v[218:221], v[32:35]
	v_mfma_f32_16x16x32_bf16 v[24:27], v[144:147], v[238:241], v[24:27]
	v_mfma_f32_16x16x32_bf16 v[16:19], v[152:155], v[238:241], v[16:19]
	v_mfma_f32_16x16x32_bf16 v[8:11], v[144:147], v[246:249], v[8:11]
	v_mfma_f32_16x16x32_bf16 v[0:3], v[152:155], v[246:249], v[0:3]
	v_mfma_f32_16x16x32_bf16 v[56:59], v[148:151], v[210:213], v[56:59]
	v_mfma_f32_16x16x32_bf16 v[48:51], v[156:159], v[210:213], v[48:51]
	v_mfma_f32_16x16x32_bf16 v[40:43], v[148:151], v[234:237], v[40:43]
	v_mfma_f32_16x16x32_bf16 v[32:35], v[156:159], v[234:237], v[32:35]
	v_mfma_f32_16x16x32_bf16 v[24:27], v[148:151], v[242:245], v[24:27]
	v_mfma_f32_16x16x32_bf16 v[16:19], v[156:159], v[242:245], v[16:19]
	v_mfma_f32_16x16x32_bf16 v[8:11], v[148:151], v[250:253], v[8:11]
	v_mfma_f32_16x16x32_bf16 v[0:3], v[156:159], v[250:253], v[0:3]
	s_setprio 0
	s_barrier
; #define PG8_STAGE(bufoff, gbase, voff) do { _Pragma("unroll") for (int _i = 0; _i < 2; ++_i) \
;         __builtin_amdgcn_global_load_lds((const unsigned*)((const char*)(gbase) + (voff)[_i]), (PG8_LAS unsigned*)(lds + (bufoff) + ldsw + _i * 8192), 16, 0, 0); } while (0)
; #define PG8_LDA(dst, b, h) do { _Pragma("unroll") for (int m = 0; m < 4; ++m) _Pragma("unroll") for (int k = 0; k < 2; ++k) dst[m][k] = *(const PG8_LAS bf16x8*)(lds + PG8_SA(b, h) + aoff + m * 2048 + k * 1024); } while (0)
; #define PG8_LDB(dst, b, h) do { _Pragma("unroll") for (int n = 0; n < 2; ++n) _Pragma("unroll") for (int k = 0; k < 2; ++k) dst[n][k] = *(const PG8_LAS bf16x8*)(lds + PG8_SB(b, h) + boff + n * 2048 + k * 1024); } while (0)
; #define PG8_MMA(ai, bj, At, Bt) do { __builtin_amdgcn_s_setprio(1); _Pragma("unroll") for (int m = 0; m < 4; ++m) _Pragma("unroll") for (int n = 0; n < 2; ++n) _Pragma("unroll") for (int k = 0; k < 2; ++k) \
;         acc[ai][bj][m][n] = __builtin_amdgcn_mfma_f32_16x16x32_bf16(Bt[n][k], At[m][k], acc[ai][bj][m][n], 0, 0, 0); __builtin_amdgcn_s_setprio(0); } while (0)
; #define PG8_WAIT_V(n) asm volatile("s_waitcnt vmcnt(" #n ")" ::: "memory")
; #define PG8_WAIT_L(n) asm volatile("s_waitcnt lgkmcnt(" #n ")" ::: "memory")
; #define PG8_BAR __builtin_amdgcn_s_barrier()
; #define PG8_SCHED __builtin_amdgcn_sched_barrier(0)
; template <class Epi, class Sched, bool ALIGN_EPI = false, bool SP2 = false>
; __device__ __forceinline__ void gemm_phase(PG8_LAS unsigned char* lds, const Gemm g, const Sched& S, const Epi& E) {
;     ...
;             PG8_LDB(B0, 1, 0); PG8_LDB(B1, 1, 1); PG8_SCHED; PG8_LDA(At, 1, 0); PG8_STAGE(PG8_SA(0, 1), a2 + hstep, voffA);
;             PG8_WAIT_V(8); PG8_WAIT_L(0); PG8_BAR; PG8_MMA(0, 0, At, B0); PG8_MMA(0, 1, At, B1); PG8_BAR; PG8_SCHED;
	s_add_i32 s29, 0, 0x18000
	s_add_i32 s50, 0, 0x1c000
	v_add_u32_e32 v140, s29, v231
	v_add_u32_e32 v156, s50, v231
	ds_read_b128 v[128:131], v140
	ds_read_b128 v[132:135], v140 offset:1024
	ds_read_b128 v[136:139], v140 offset:2048
	ds_read_b128 v[140:143], v140 offset:3072
	ds_read_b128 v[144:147], v156
	ds_read_b128 v[148:151], v156 offset:1024
	ds_read_b128 v[152:155], v156 offset:2048
	ds_read_b128 v[156:159], v156 offset:3072
	s_add_u32 s92, s92, s21
	s_addc_u32 s93, s93, 0
	s_mov_b32 m0, s45
	v_lshl_add_u64 v[214:215], s[92:93], 0, v[174:175]
	ds_read_b128 v[160:163], v233 offset:32768
	ds_read_b128 v[210:213], v233 offset:33792
	ds_read_b128 v[218:221], v233 offset:34816
	ds_read_b128 v[234:237], v233 offset:35840
	ds_read_b128 v[238:241], v233 offset:36864
	ds_read_b128 v[242:245], v233 offset:37888
	ds_read_b128 v[246:249], v233 offset:38912
	ds_read_b128 v[250:253], v233 offset:39936
	global_load_lds_dwordx4 v[214:215], off
	v_lshl_add_u64 v[214:215], s[92:93], 0, v[176:177]
	s_mov_b32 m0, s57
	s_nop 0
	global_load_lds_dwordx4 v[214:215], off
	s_waitcnt vmcnt(8)
	s_waitcnt lgkmcnt(0)
	s_barrier
	s_setprio 1
	s_waitcnt lgkmcnt(0)
	v_mfma_f32_16x16x32_bf16 v[124:127], v[128:131], v[160:163], v[124:127]
	v_mfma_f32_16x16x32_bf16 v[116:119], v[136:139], v[160:163], v[116:119]
	v_mfma_f32_16x16x32_bf16 v[108:111], v[128:131], v[218:221], v[108:111]
	v_mfma_f32_16x16x32_bf16 v[100:103], v[136:139], v[218:221], v[100:103]
	v_mfma_f32_16x16x32_bf16 v[92:95], v[128:131], v[238:241], v[92:95]
	v_mfma_f32_16x16x32_bf16 v[84:87], v[136:139], v[238:241], v[84:87]
	v_mfma_f32_16x16x32_bf16 v[76:79], v[128:131], v[246:249], v[76:79]
	v_mfma_f32_16x16x32_bf16 v[68:71], v[136:139], v[246:249], v[68:71]
	v_mfma_f32_16x16x32_bf16 v[124:127], v[132:135], v[210:213], v[124:127]
	v_mfma_f32_16x16x32_bf16 v[116:119], v[140:143], v[210:213], v[116:119]
	v_mfma_f32_16x16x32_bf16 v[108:111], v[132:135], v[234:237], v[108:111]
	v_mfma_f32_16x16x32_bf16 v[100:103], v[140:143], v[234:237], v[100:103]
	v_mfma_f32_16x16x32_bf16 v[92:95], v[132:135], v[242:245], v[92:95]
	v_mfma_f32_16x16x32_bf16 v[84:87], v[140:143], v[242:245], v[84:87]
	v_mfma_f32_16x16x32_bf16 v[76:79], v[132:135], v[250:253], v[76:79]
	v_mfma_f32_16x16x32_bf16 v[68:71], v[140:143], v[250:253], v[68:71]
	s_setprio 0
	s_setprio 1
	v_mfma_f32_16x16x32_bf16 v[120:123], v[144:147], v[160:163], v[120:123]
	v_mfma_f32_16x16x32_bf16 v[112:115], v[152:155], v[160:163], v[112:115]
	v_mfma_f32_16x16x32_bf16 v[104:107], v[144:147], v[218:221], v[104:107]
	v_mfma_f32_16x16x32_bf16 v[96:99], v[152:155], v[218:221], v[96:99]
	v_mfma_f32_16x16x32_bf16 v[88:91], v[144:147], v[238:241], v[88:91]
	v_mfma_f32_16x16x32_bf16 v[80:83], v[152:155], v[238:241], v[80:83]
	v_mfma_f32_16x16x32_bf16 v[72:75], v[144:147], v[246:249], v[72:75]
	v_mfma_f32_16x16x32_bf16 v[64:67], v[152:155], v[246:249], v[64:67]
	v_mfma_f32_16x16x32_bf16 v[120:123], v[148:151], v[210:213], v[120:123]
	v_mfma_f32_16x16x32_bf16 v[112:115], v[156:159], v[210:213], v[112:115]
	v_mfma_f32_16x16x32_bf16 v[104:107], v[148:151], v[234:237], v[104:107]
	v_mfma_f32_16x16x32_bf16 v[96:99], v[156:159], v[234:237], v[96:99]
	v_mfma_f32_16x16x32_bf16 v[88:91], v[148:151], v[242:245], v[88:91]
	v_mfma_f32_16x16x32_bf16 v[80:83], v[156:159], v[242:245], v[80:83]
	v_mfma_f32_16x16x32_bf16 v[72:75], v[148:151], v[250:253], v[72:75]
	v_mfma_f32_16x16x32_bf16 v[64:67], v[156:159], v[250:253], v[64:67]
	s_setprio 0
	s_barrier
; #define PG8_STAGE(bufoff, gbase, voff) do { _Pragma("unroll") for (int _i = 0; _i < 2; ++_i) \
;         __builtin_amdgcn_global_load_lds((const unsigned*)((const char*)(gbase) + (voff)[_i]), (PG8_LAS unsigned*)(lds + (bufoff) + ldsw + _i * 8192), 16, 0, 0); } while (0)
; #define PG8_LDA(dst, b, h) do { _Pragma("unroll") for (int m = 0; m < 4; ++m) _Pragma("unroll") for (int k = 0; k < 2; ++k) dst[m][k] = *(const PG8_LAS bf16x8*)(lds + PG8_SA(b, h) + aoff + m * 2048 + k * 1024); } while (0)
; #define PG8_MMA(ai, bj, At, Bt) do { __builtin_amdgcn_s_setprio(1); _Pragma("unroll") for (int m = 0; m < 4; ++m) _Pragma("unroll") for (int n = 0; n < 2; ++n) _Pragma("unroll") for (int k = 0; k < 2; ++k) \
;         acc[ai][bj][m][n] = __builtin_amdgcn_mfma_f32_16x16x32_bf16(Bt[n][k], At[m][k], acc[ai][bj][m][n], 0, 0, 0); __builtin_amdgcn_s_setprio(0); } while (0)
; #define PG8_WAIT_V(n) asm volatile("s_waitcnt vmcnt(" #n ")" ::: "memory")
; #define PG8_WAIT_L(n) asm volatile("s_waitcnt lgkmcnt(" #n ")" ::: "memory")
; #define PG8_BAR __builtin_amdgcn_s_barrier()
; #define PG8_SCHED __builtin_amdgcn_sched_barrier(0)
; template <class Epi, class Sched, bool ALIGN_EPI = false, bool SP2 = false>
; __device__ __forceinline__ void gemm_phase(PG8_LAS unsigned char* lds, const Gemm g, const Sched& S, const Epi& E) {
;     ...
;         const bool has_next = S.next(ui + 1, nxt);
;         const char* nA = has_next ? (const char*)g.A + (size_t)nxt.pm * tstep + (size_t)(nxt.ko / BK) * kstep : cA; const char* nB = has_next ? (const char*)g.Bt + (size_t)nxt.pn * tstep + (size_t)(nxt.ko / BK) * kstep : cB;
;         for (int t = 0; t < nt; t += 2) {
;             const bool last = (t == nt - 2);
;             const char* a1 = cA + (size_t)(t + 1) * kstep;
;             const char* a2 = last ? nA : cA + (size_t)(t + 2) * kstep; const char* b2 = last ? nB : cB + (size_t)(t + 2) * kstep;
;             const char* a3 = a2 + kstep; const char* b3 = b2 + kstep;
;     ...
;             PG8_LDA(At, 1, 1); PG8_STAGE(PG8_SB(1, 0), b3, voffB); PG8_STAGE(PG8_SB(1, 1), b3 + hstep, voffB); PG8_STAGE(PG8_SA(1, 0), a3, voffA);
;             PG8_WAIT_V(8); PG8_WAIT_L(0); PG8_BAR; PG8_MMA(1, 0, At, B0); PG8_MMA(1, 1, At, B1); PG8_BAR; PG8_SCHED;
	s_add_u32 s30, s30, s20
	s_addc_u32 s31, s31, 0
	s_add_i32 s29, s29, s77
	v_lshl_add_u64 v[214:215], s[30:31], 0, v[174:175]
	s_mov_b32 m0, s29
	ds_read_b128 v[160:163], v233 offset:49152
	ds_read_b128 v[210:213], v233 offset:50176
	ds_read_b128 v[218:221], v233 offset:51200
	ds_read_b128 v[234:237], v233 offset:52224
	ds_read_b128 v[238:241], v233 offset:53248
	ds_read_b128 v[242:245], v233 offset:54272
	ds_read_b128 v[246:249], v233 offset:55296
	ds_read_b128 v[250:253], v233 offset:56320
	global_load_lds_dwordx4 v[214:215], off
	s_add_i32 m0, s29, 0x2000
	v_lshl_add_u64 v[214:215], s[30:31], 0, v[176:177]
	s_add_u32 s30, s30, s21
	s_addc_u32 s31, s31, 0
	s_add_i32 s29, s50, s77
	global_load_lds_dwordx4 v[214:215], off
	v_lshl_add_u64 v[214:215], s[30:31], 0, v[174:175]
	s_mov_b32 m0, s29
	s_nop 0
	global_load_lds_dwordx4 v[214:215], off
	v_lshl_add_u64 v[214:215], s[30:31], 0, v[176:177]
	s_add_i32 m0, s29, 0x2000
	s_nop 0
	global_load_lds_dwordx4 v[214:215], off
	v_lshl_add_u64 v[214:215], s[12:13], 0, v[174:175]
	s_mov_b32 m0, s74
	s_nop 0
	global_load_lds_dwordx4 v[214:215], off
	v_lshl_add_u64 v[214:215], s[12:13], 0, v[176:177]
	s_mov_b32 m0, s75
	s_nop 0
	global_load_lds_dwordx4 v[214:215], off
	s_waitcnt vmcnt(8)
	s_waitcnt lgkmcnt(0)
	s_barrier
	s_setprio 1
	s_waitcnt lgkmcnt(0)
	v_mfma_f32_16x16x32_bf16 v[60:63], v[128:131], v[160:163], v[60:63]
	v_mfma_f32_16x16x32_bf16 v[52:55], v[136:139], v[160:163], v[52:55]
	s_cmp_ge_u32 s14, s62
	s_cselect_b32 s100, 1, 0
	v_mfma_f32_16x16x32_bf16 v[44:47], v[128:131], v[218:221], v[44:47]
	s_mov_b64 s[12:13], s[14:15]
	v_mfma_f32_16x16x32_bf16 v[36:39], v[136:139], v[218:221], v[36:39]
	s_add_u32 s94, s12, 1
	s_addc_u32 s95, s13, 0
	v_mfma_f32_16x16x32_bf16 v[28:31], v[128:131], v[238:241], v[28:31]
	s_add_u32 s14, s12, 2
	s_addc_u32 s15, s13, 0
	v_mfma_f32_16x16x32_bf16 v[20:23], v[136:139], v[238:241], v[20:23]
	s_lshl_b64 s[30:31], s[14:15], s60
	v_mfma_f32_16x16x32_bf16 v[12:15], v[128:131], v[246:249], v[12:15]
	s_add_u32 s13, s10, s30
	s_addc_u32 s29, s11, s31
	v_mfma_f32_16x16x32_bf16 v[4:7], v[136:139], v[246:249], v[4:7]
	s_add_u32 s30, s8, s30
	s_addc_u32 s31, s9, s31
	v_mfma_f32_16x16x32_bf16 v[60:63], v[132:135], v[210:213], v[60:63]
	s_cmp_eq_u32 s2, s12
	s_cselect_b32 s92, s88, s13
	s_cselect_b32 s93, s89, s29
	s_cselect_b32 s30, s90, s30
	s_cselect_b32 s31, s91, s31
	v_mfma_f32_16x16x32_bf16 v[52:55], v[140:143], v[210:213], v[52:55]
	s_add_u32 s12, s92, s20
	s_addc_u32 s13, s93, 0
	v_mfma_f32_16x16x32_bf16 v[44:47], v[132:135], v[234:237], v[44:47]
	s_add_i32 s29, 0, 0x10000
	v_mfma_f32_16x16x32_bf16 v[36:39], v[140:143], v[234:237], v[36:39]
	s_add_i32 s50, 0, 0x14000
	v_mfma_f32_16x16x32_bf16 v[28:31], v[132:135], v[242:245], v[28:31]
	s_lshl_b64 s[94:95], s[94:95], s60
	v_mfma_f32_16x16x32_bf16 v[20:23], v[140:143], v[242:245], v[20:23]
	s_add_u32 s94, s25, s94
	s_addc_u32 s95, s26, s95
	v_mfma_f32_16x16x32_bf16 v[12:15], v[132:135], v[250:253], v[12:15]
	v_mfma_f32_16x16x32_bf16 v[4:7], v[140:143], v[250:253], v[4:7]
	s_setprio 0
	s_setprio 1
	v_mfma_f32_16x16x32_bf16 v[56:59], v[144:147], v[160:163], v[56:59]
	v_mfma_f32_16x16x32_bf16 v[48:51], v[152:155], v[160:163], v[48:51]
	v_mfma_f32_16x16x32_bf16 v[40:43], v[144:147], v[218:221], v[40:43]
	v_mfma_f32_16x16x32_bf16 v[32:35], v[152:155], v[218:221], v[32:35]
	v_mfma_f32_16x16x32_bf16 v[24:27], v[144:147], v[238:241], v[24:27]
	v_mfma_f32_16x16x32_bf16 v[16:19], v[152:155], v[238:241], v[16:19]
	v_mfma_f32_16x16x32_bf16 v[8:11], v[144:147], v[246:249], v[8:11]
	v_mfma_f32_16x16x32_bf16 v[0:3], v[152:155], v[246:249], v[0:3]
	v_mfma_f32_16x16x32_bf16 v[56:59], v[148:151], v[210:213], v[56:59]
	v_mfma_f32_16x16x32_bf16 v[48:51], v[156:159], v[210:213], v[48:51]
	v_mfma_f32_16x16x32_bf16 v[40:43], v[148:151], v[234:237], v[40:43]
	v_mfma_f32_16x16x32_bf16 v[32:35], v[156:159], v[234:237], v[32:35]
	v_mfma_f32_16x16x32_bf16 v[24:27], v[148:151], v[242:245], v[24:27]
	v_mfma_f32_16x16x32_bf16 v[16:19], v[156:159], v[242:245], v[16:19]
	v_mfma_f32_16x16x32_bf16 v[8:11], v[148:151], v[250:253], v[8:11]
	v_mfma_f32_16x16x32_bf16 v[0:3], v[156:159], v[250:253], v[0:3]
	s_setprio 0
	s_barrier
	s_cmp_eq_u32 s100, 0
	s_cbranch_scc1 .LBB0_162
	s_and_b64 vcc, exec, s[86:87]
	s_cbranch_vccz .LBB0_167
	s_barrier
	s_cmp_lt_i32 s58, 1
	s_mov_b64 s[8:9], -1
	s_cbranch_scc0 .LBB0_168
